# attention key loop: one static s_setprio raise for the second wave of each SIMD
# baseline (speedup 1.0000x reference)
.Lat_bar2:
	s_barrier
	s_cmp_lt_u32 s3, 4
	s_cbranch_scc1 .Lat_prio_10
	s_setprio 1
.Lat_prio_10:
	s_lshl_b32 s4, s57, 5
	s_add_u32 s4, s4, s70
	s_add_u32 s4, s4, s83
	s_cmpk_ge_u32 s4, 0x180
	s_cselect_b32 s5, 0x180, 0
	s_sub_u32 s69, s4, s5
	s_mul_i32 s4, s69, 0x90
	v_add_u32_e32 v216, s4, v8
	v_add_u32_e32 v217, s4, v9
	ds_read_b128 v[148:151], v216 offset:0
	ds_read_b128 v[152:155], v216 offset:32
	ds_read_b128 v[156:159], v216 offset:64
	ds_read_b128 v[160:163], v216 offset:96
	ds_read_b64_tr_b16 v[176:177], v217 offset:0
	ds_read_b64_tr_b16 v[178:179], v217 offset:1152
	ds_read_b64_tr_b16 v[180:181], v217 offset:2304
	ds_read_b64_tr_b16 v[182:183], v217 offset:3456
	ds_read_b64_tr_b16 v[184:185], v217 offset:64
	ds_read_b64_tr_b16 v[186:187], v217 offset:1216
	ds_read_b64_tr_b16 v[188:189], v217 offset:2368
	ds_read_b64_tr_b16 v[190:191], v217 offset:3520

.Lat_jnext_12:
	s_mov_b32 s69, s84
	s_add_u32 s57, s57, 1
	s_cmp_lt_u32 s57, s68
	s_cbranch_scc1 .Lat_jloop_11
	s_waitcnt lgkmcnt(0)
	s_setprio 0
